# phase 2b work queue: next item's index fetched one item ahead (atomic issued into a free spill lane after publishing the current index)
# baseline (speedup 1.0000x reference)
; DI int next_item(unsigned* ctr, int* slot) {
;   __syncthreads();
;   if (threadIdx.x == 0) *slot = (int)atomicAdd(ctr, 1u);
;   __syncthreads();
;   return *slot;
; }
; __global__ void __launch_bounds__(256, 2) mega(Params p) {
;     ...
;         int it;
;         if (first) { it = (int)blockIdx.x; first = false; }
;         else it = next_item(ctr + layer * 2 + 1 + 8 * rep, &slot) + (int)gridDim.x;
.Lmap2b_done:
	v_writelane_b32 v255, 0, 53
	s_nop 0
	s_nop 0
	s_nop 0
	s_nop 0
	s_nop 0
	s_nop 0
	s_nop 0
	s_nop 0
	s_nop 0
	s_nop 0
	s_nop 0
	s_nop 0
	s_nop 0
	s_nop 0
	s_nop 0
	s_nop 0
	s_nop 0
	s_nop 0
	s_nop 0
	s_nop 0
	s_nop 0
	s_nop 0
	s_nop 0
	s_nop 0
	s_nop 0
	s_nop 0
	s_nop 0
	s_nop 0
	s_nop 0
	s_nop 0
	s_nop 0
	s_nop 0
	s_nop 0
	s_nop 0
	s_nop 0
	s_nop 0
	s_nop 0
	s_nop 0
	s_nop 0
	s_nop 0
	s_nop 0
	s_nop 0
	s_nop 0
	s_nop 0
	s_nop 0
	s_nop 0
	s_nop 0
	s_nop 0
	s_branch .LBB0_358
.LBB0_355:
	s_or_b64 exec, exec, s[6:7]
	s_waitcnt vmcnt(0)
	v_readfirstlane_b32 s2, v1
	s_nop 1
	v_add_u32_e32 v0, s2, v0
	ds_write_b32 v161, v0 offset:16
	s_mov_b64 s[6:7], exec
	v_readlane_b32 s98, v255, 43
	v_readlane_b32 s99, v255, 44
	s_mov_b32 exec_lo, 0
	s_mov_b32 exec_hi, 0x100000
	s_nop 4
	global_atomic_add v255, v161, v183, s[98:99] offset:4 sc0
	s_mov_b64 exec, s[6:7]
	v_writelane_b32 v255, 1, 53

; DI int next_item(unsigned* ctr, int* slot) {
;   __syncthreads();
;   if (threadIdx.x == 0) *slot = (int)atomicAdd(ctr, 1u);
;   __syncthreads();
;   return *slot;
; }
.LBB0_609:
	s_setprio 0
	s_waitcnt lgkmcnt(0)
	s_barrier
	s_mov_b64 s[0:1], exec
	v_readlane_b32 s6, v252, 1
	v_readlane_b32 s7, v252, 2
	v_readlane_b32 s64, v255, 38
	s_and_b64 s[6:7], s[0:1], s[6:7]
	v_readlane_b32 s65, v255, 39
	s_xor_b64 s[0:1], s[6:7], s[0:1]
	v_readlane_b32 s65, v255, 40
	s_mov_b32 s66, 0x20000
	s_mov_b32 s67, 0x40000
	s_mov_b32 s68, 0x60000
	v_readlane_b32 s69, v255, 50
	s_mov_b32 s70, 0x3fd744fd
	s_mov_b64 exec, s[6:7]
	s_cbranch_execz .LBB0_356
	s_mov_b64 s[8:9], exec
	s_waitcnt vmcnt(6)
	v_mbcnt_lo_u32_b32 v0, s8, 0
	v_mbcnt_hi_u32_b32 v0, s9, v0
	v_cmp_eq_u32_e32 vcc, 0, v0
	s_and_saveexec_b64 s[6:7], vcc
	s_cbranch_execz .LBB0_355
	s_bcnt1_i32_b64 s2, s[8:9]
	v_readlane_b32 s8, v255, 43
	v_mov_b32_e32 v1, s2
	v_readlane_b32 s9, v255, 44
	v_readlane_b32 s98, v255, 53
	s_cmp_eq_u32 s98, 0
	s_cbranch_scc1 .Lqp_sync
	s_waitcnt vmcnt(0)
	v_readlane_b32 s98, v255, 52
	s_nop 1
	v_mov_b32_e32 v1, s98
	s_branch .LBB0_355
.Lqp_sync:
	s_nop 4
	global_atomic_add v1, v161, v1, s[8:9] offset:4 sc0
	s_branch .LBB0_355
	s_nop 0
	s_nop 0
	s_nop 0
	s_nop 0
	s_nop 0
	s_nop 0
	s_nop 0
	s_nop 0
	s_nop 0
	s_nop 0
	s_nop 0
	s_nop 0
	s_nop 0
	s_nop 0
	s_nop 0
	s_nop 0
	s_nop 0
	s_nop 0
	s_nop 0
	s_nop 0
	s_nop 0
	s_nop 0
	s_nop 0
	s_nop 0
	s_nop 0
	s_nop 0
	s_nop 0
	s_nop 0
	s_nop 0
	s_nop 0
	s_nop 0
	s_nop 0
	s_nop 0
	s_nop 0
	s_nop 0
	s_nop 0
	s_nop 0
	s_nop 0
	s_nop 0
	s_nop 0
	s_nop 0
	s_nop 0
	s_nop 0
	s_nop 0
	s_nop 0
	s_nop 0
	s_nop 0
	s_nop 0
	s_nop 0
	s_nop 0
	s_nop 0
	s_nop 0
	s_nop 0
	s_nop 0
